# dn_prep: loop-invariant exp(a_log)/dt_bias hoisted out of the item loop; per-item decay/beta logits prefetched during the previous item (wave-0 critical path)
# speedup vs baseline: 1.0105x; 1.0105x over previous
; DI void dn_prep_item(const Params& p, int l, int item, int next_item, u32x4 (&pre)[12], unsigned char* lds, int tid) {
;     float zz = 0.f; asm volatile("" : "+v"(zz));
;     const int h = item & 7, n = (item >> 3) & 31, b = item >> 8, lane = tid & 63;
;     float* Qs = (float*)lds; float* Ks = Qs + 4160; float* Vs = Ks + 4160; float* Ls = Vs + 4160; float* AIs = Ls + 4096; float* XS = AIs + 4096;
;     float* Gs = XS + 64 * 129; float* BETAs = Gs + 64; float* EGs = BETAs + 64;
;     bf16_t* KH = (bf16_t*)(EGs + 64); bf16_t* KL = KH + 64 * 72; bf16_t* QH = KL + 64 * 72; bf16_t* QL = QH + 64 * 72;
;     const float* DAB = (const float*)(p.ws + OFF_DAB);
;     const float* cw = p.in[12] + (size_t)l * 4 * 1536;
;     float da_raw = 0.f, db_raw = 0.f, dtb = 0.f, alog = 0.f;
;     if (tid < 64) { const size_t tok = (size_t)b * SEQL + n * 64 + tid; da_raw = DAB[tok * 16 + h]; db_raw = DAB[tok * 16 + 8 + h]; dtb = p.in[14][l * 8 + h]; alog = p.in[13][l * 8 + h]; }
; __global__ void __launch_bounds__(512, 2) mega_fwd(Params p) {
;     ...
;             { u32x4 pre[12]; dn_prep_fetch(P, bx < 2048 ? bx : 0, tid, pre);
;               for (int it = bx; it < 2048; it += G) { int tl = tid; asm volatile("" : "+v"(tl)); dn_prep_item(P, l, it, it + G, pre, lds, tl); } }
.LBB0_274:
	s_and_b64 vcc, exec, s[6:7]
	s_cbranch_vccz .LBB0_745
	s_cmp_gt_i32 s63, 2
	s_mov_b64 s[6:7], -1
	s_cbranch_scc0 .LBB0_741
	s_cmp_gt_i32 s63, 3
	s_mov_b64 s[26:27], -1
	s_cbranch_scc0 .LBB0_740
	s_cmp_gt_i32 s63, 4
	s_mov_b64 s[4:5], -1
	s_cbranch_scc0 .LBB0_506
	s_cmpk_gt_i32 s28, 0x7ff
	s_cbranch_scc1 .LBB0_505
	s_add_u32 s29, s96, 0x8180000
	s_addc_u32 s40, s97, 0
	s_lshl_b32 s4, s28, 7
	s_and_b32 s4, s4, 0x380
	s_add_u32 s4, s29, s4
	v_lshlrev_b32_e32 v0, 4, v166
	s_addc_u32 s5, s40, 0
	v_and_b32_e32 v164, 0x70, v0
	v_lshl_add_u64 v[0:1], s[4:5], 0, v[164:165]
	s_lshl_b32 s4, s28, 3
	s_and_b32 s5, s4, 0x7c0
	s_waitcnt vmcnt(0)
	v_ashrrev_i32_e32 v2, 3, v166
	s_waitcnt vmcnt(9)
	v_add_u32_e32 v4, s5, v2
	v_max_i32_e32 v2, 0, v4
	v_add_u32_e32 v4, -3, v4
	s_and_b32 s6, s4, 0xfffff800
	v_max_i32_e32 v5, -2, v4
	s_movk_i32 s7, 0xc00
	v_add3_u32 v5, v5, s6, 2
	s_waitcnt vmcnt(8)
	v_mad_i64_i32 v[10:11], s[4:5], v5, s7, v[0:1]
	v_max_i32_e32 v5, -1, v4
	v_add_u32_e32 v2, s6, v2
	v_add3_u32 v5, v5, s6, 1
	v_max_i32_e32 v4, 0, v4
	v_mad_i64_i32 v[2:3], s[4:5], v2, s7, v[0:1]
	s_waitcnt vmcnt(7)
	v_mad_i64_i32 v[12:13], s[4:5], v5, s7, v[0:1]
	v_add_u32_e32 v4, s6, v4
	v_mad_i64_i32 v[0:1], s[4:5], v4, s7, v[0:1]
	global_load_dwordx4 v[6:9], v[10:11], off offset:2048
	global_load_dwordx4 v[22:25], v[10:11], off offset:1024
	global_load_dwordx4 v[14:17], v[0:1], off offset:2048
	global_load_dwordx4 v[30:33], v[0:1], off offset:1024
	global_load_dwordx4 v[18:21], v[2:3], off offset:1024
	global_load_dwordx4 v[34:37], v[2:3], off
	s_nop 0
	global_load_dwordx4 v[2:5], v[2:3], off offset:2048
	s_nop 0
	global_load_dwordx4 v[38:41], v[10:11], off
	global_load_dwordx4 v[26:29], v[12:13], off offset:1024
	global_load_dwordx4 v[42:45], v[12:13], off
	s_nop 0
	global_load_dwordx4 v[10:13], v[12:13], off offset:2048
	s_nop 0
	global_load_dwordx4 v[46:49], v[0:1], off
	s_add_u32 s16, s96, 0x200000
	s_addc_u32 s17, s97, 0
	s_lshl_b32 s41, s20, 3
	s_add_u32 s26, s96, 0x1980000
	s_addc_u32 s27, s97, 0
	s_add_u32 s38, s96, 0x1a0000
	v_add_u32_e32 v51, 0xc300, v168
	v_add_u32_e32 v53, 0x10300, v168
	v_add_u32_e32 v50, 0x14300, v168
	v_add_u32_e32 v68, 0x1c400, v168
	v_add_u32_e32 v69, 0x1c500, v168
	v_add_u32_e32 v70, 0x1c600, v168
	v_add_u32_e32 v71, 0x1c700, v168
	v_add_u32_e32 v72, 0x1eb00, v168
	v_add_u32_e32 v73, 0x20f00, v168
	v_add_u32_e32 v74, 0x23300, v168
	v_add_u32_e32 v52, 0x25700, v168
	v_add_u32_e32 v75, 0x1c4fc, v168
	s_addc_u32 s39, s97, 0
	v_add_u32_e32 v76, 0x1c6fc, v168
	s_load_dwordx4 s[12:15], s[0:1], 0x68
	s_and_b32 s4, s28, 7
	s_or_b32 s22, s4, s41
	s_ashr_i32 s23, s22, 31
	s_lshl_b64 s[22:23], s[22:23], 2
	s_waitcnt lgkmcnt(0)
	s_add_u32 s14, s14, s22
	s_addc_u32 s15, s15, s23
	s_add_u32 s12, s12, s22
	s_addc_u32 s13, s13, s23
	global_load_dword v201, v165, s[14:15]
	global_load_dword v200, v165, s[12:13]
	s_ashr_i32 s8, s28, 8
	s_lshl_b32 s8, s8, 11
	s_bfe_u32 s9, s28, 0x50003
	s_lshl_b32 s9, s9, 6
	s_or_b32 s8, s8, s9
	s_lshl_b32 s9, s4, 2
	v_and_b32_e32 v142, 63, v166
	v_add_u32_e32 v142, s8, v142
	v_lshlrev_b32_e32 v142, 6, v142
	v_add_u32_e32 v142, s9, v142
	global_load_dword v202, v142, s[16:17]
	global_load_dword v203, v142, s[16:17] offset:32
	s_waitcnt vmcnt(2)
	v_mul_f32_e32 v143, 0x3fb8aa3b, v200
	v_fma_f32 v158, v200, s88, -v143
	v_rndne_f32_e32 v159, v143
	v_fmac_f32_e32 v158, 0x32a5705f, v200
	v_sub_f32_e32 v143, v143, v159
	v_add_f32_e32 v143, v143, v158
	v_exp_f32_e32 v143, v143
	v_cvt_i32_f32_e32 v158, v159
	v_cmp_ngt_f32_e32 vcc, s79, v200
	v_ldexp_f32 v143, v143, v158
	s_nop 0
	v_cndmask_b32_e32 v143, 0, v143, vcc
	v_cmp_nlt_f32_e32 vcc, s54, v200
	s_nop 1
	v_cndmask_b32_e32 v200, v210, v143, vcc
	s_mov_b32 s42, s28
	s_branch .LBB0_281

; DI void dn_prep_item(const Params& p, int l, int item, int next_item, u32x4 (&pre)[12], unsigned char* lds, int tid) {
;     float zz = 0.f; asm volatile("" : "+v"(zz));
;     const int h = item & 7, n = (item >> 3) & 31, b = item >> 8, lane = tid & 63;
;     float* Qs = (float*)lds; float* Ks = Qs + 4160; float* Vs = Ks + 4160; float* Ls = Vs + 4160; float* AIs = Ls + 4096; float* XS = AIs + 4096;
;     float* Gs = XS + 64 * 129; float* BETAs = Gs + 64; float* EGs = BETAs + 64;
;     bf16_t* KH = (bf16_t*)(EGs + 64); bf16_t* KL = KH + 64 * 72; bf16_t* QH = KL + 64 * 72; bf16_t* QL = QH + 64 * 72;
;     const float* DAB = (const float*)(p.ws + OFF_DAB);
;     const float* cw = p.in[12] + (size_t)l * 4 * 1536;
;     float da_raw = 0.f, db_raw = 0.f, dtb = 0.f, alog = 0.f;
;     if (tid < 64) { const size_t tok = (size_t)b * SEQL + n * 64 + tid; da_raw = DAB[tok * 16 + h]; db_raw = DAB[tok * 16 + 8 + h]; dtb = p.in[14][l * 8 + h]; alog = p.in[13][l * 8 + h]; }
.LBB0_281:
	v_mov_b32_e32 v54, v166
	v_mov_b32_e32 v0, v165
	s_bfe_u32 s43, s42, 0x50003
	v_cmp_gt_i32_e64 s[6:7], 64, v54
	v_cmp_lt_i32_e32 vcc, 63, v54
	s_and_saveexec_b64 s[4:5], vcc
	s_xor_b64 s[4:5], exec, s[4:5]
	s_lshl_b32 s12, s43, 6
	s_or_saveexec_b64 s[10:11], s[4:5]
	s_load_dwordx2 s[8:9], s[0:1], 0x60
	s_and_b32 s4, s42, 7
	v_mov_b32_e32 v66, 0
	v_mov_b32_e32 v80, 1.0
	v_mov_b32_e32 v1, s12
	v_ashrrev_i32_e32 v55, 31, v54
	v_mov_b32_e32 v81, 0
	v_mov_b32_e32 v78, 0
	v_mov_b32_e32 v79, 0
	s_xor_b64 exec, exec, s[10:11]
	s_cbranch_execz .LBB0_285
	s_lshl_b32 s5, s43, 6
	v_mov_b32_e32 v1, s5

; DI unsigned pk2(float lo, float hi) { f32x2_t v = {lo, hi}; bf16x2_t b = __builtin_convertvector(v, bf16x2_t); return __builtin_bit_cast(unsigned, b); }
; DI float silu_f(float x) { return x * __builtin_amdgcn_rcpf(1.f + __builtin_amdgcn_exp2f(-1.4426950408889634f * x)); }
; DI void unpack8(u32x4 w, float* f) { f[0] = bflo(w.x); f[1] = bfhi(w.x); f[2] = bflo(w.y); f[3] = bfhi(w.y); f[4] = bflo(w.z); f[5] = bfhi(w.z); f[6] = bflo(w.w); f[7] = bfhi(w.w); }
; DI void dn_prep_item(const Params& p, int l, int item, int next_item, u32x4 (&pre)[12], unsigned char* lds, int tid) {
;     ...
;             for (int e = 0; e < 8; ++e) { a[e] = silu_f(a[e]); ss += a[e] * a[e]; }
;             float sc = 1.f;
;             if (mat < 2) { ss += __shfl_xor(ss, 1); ss += __shfl_xor(ss, 2); ss += __shfl_xor(ss, 4); sc = rsqrtf(ss + EPSF) * (mat == 0 ? 0.125f : 1.f); }
;             float* dst = (mat == 0 ? Qs : (mat == 1 ? Ks : Vs)) + i * 65 + d0;
; #pragma unroll
;             for (int e = 0; e < 8; ++e) { a[e] *= sc; dst[e] = a[e]; }
;             if (mat < 2) { float hf[8], lo[8]; u32x4 wh, wl;
;                 wh.x = pk2(a[0], a[1]); wh.y = pk2(a[2], a[3]); wh.z = pk2(a[4], a[5]); wh.w = pk2(a[6], a[7]); unpack8(wh, hf);
; #pragma unroll
;                 for (int e = 0; e < 8; ++e) lo[e] = a[e] - hf[e];
;                 wl.x = pk2(lo[0], lo[1]); wl.y = pk2(lo[2], lo[3]); wl.z = pk2(lo[4], lo[5]); wl.w = pk2(lo[6], lo[7]);
;                 *(u32x4*)((mat == 0 ? QH : KH) + i * 72 + d0) = wh; *(u32x4*)((mat == 0 ? QL : KL) + i * 72 + d0) = wl; } }
;         { f32x4* z = (f32x4*)AIs + tid * 2; z[0] = (f32x4){zz, zz, zz, zz}; z[1] = (f32x4){zz, zz, zz, zz}; }
;     }
;     if (tid < 64) {
;         const float a = da_raw + dtb, bb = db_raw;
;         const float sp = (a > 20.f) ? a : ((a < -15.f) ? expf(a) : logf(1.f + expf(a)));
.LBB0_309:
	s_or_b64 exec, exec, s[8:9]
	v_mul_f32_e32 v2, 0xbfb8aa3b, v25
	v_exp_f32_e32 v2, v2
	v_mul_f32_e32 v3, 0xbfb8aa3b, v20
	v_exp_f32_e32 v4, v3
	v_and_b32_e32 v30, 63, v54
	v_add_f32_e32 v2, 1.0, v2
	v_rcp_f32_e32 v3, v2
	v_add_f32_e32 v2, 1.0, v4
	v_mul_f32_e32 v4, 0xbfb8aa3b, v21
	v_exp_f32_e32 v5, v4
	v_mul_f32_e32 v4, 0xbfb8aa3b, v22
	v_exp_f32_e32 v6, v4
	v_rcp_f32_e32 v4, v2
	v_add_f32_e32 v2, 1.0, v5
	v_rcp_f32_e32 v5, v2
	v_add_f32_e32 v2, 1.0, v6
	v_mul_f32_e32 v6, 0xbfb8aa3b, v23
	v_exp_f32_e32 v7, v6
	v_mul_f32_e32 v6, 0xbfb8aa3b, v18
	v_exp_f32_e32 v8, v6
	v_rcp_f32_e32 v6, v2
	v_add_f32_e32 v2, 1.0, v7
	v_rcp_f32_e32 v7, v2
	v_add_f32_e32 v2, 1.0, v8
	v_mul_f32_e32 v8, 0xbfb8aa3b, v19
	v_exp_f32_e32 v9, v8
	v_mul_f32_e32 v8, 0xbfb8aa3b, v24
	v_exp_f32_e32 v10, v8
	v_rcp_f32_e32 v8, v2
	v_add_f32_e32 v2, 1.0, v9
	v_rcp_f32_e32 v9, v2
	v_add_f32_e32 v2, 1.0, v10
	v_rcp_f32_e32 v2, v2
	v_add_u32_e32 v10, 0x8200, v1
	v_pk_mul_f32 v[4:5], v[20:21], v[4:5]
	ds_write2_b32 v10, v4, v5 offset1:1
	v_add_u32_e32 v10, 0x8208, v1
	v_pk_mul_f32 v[4:5], v[22:23], v[6:7]
	ds_write2_b32 v10, v4, v5 offset1:1
	v_add_u32_e32 v6, 0x8210, v1
	v_pk_mul_f32 v[4:5], v[18:19], v[8:9]
	v_add_u32_e32 v1, 0x8218, v1
	v_pk_mul_f32 v[2:3], v[24:25], v[2:3]
	ds_write2_b32 v6, v4, v5 offset1:1
	ds_write2_b32 v1, v2, v3 offset1:1
	v_lshl_add_u32 v4, v54, 5, v53
	v_mov_b32_e32 v1, v0
	v_mov_b32_e32 v2, v0
	v_mov_b32_e32 v3, v0
	ds_write_b128 v4, v[0:3]
	ds_write_b128 v4, v[0:3] offset:16
	s_and_saveexec_b64 s[8:9], s[6:7]
	s_cbranch_execz .LBB0_315
	v_add_f32_e32 v4, v201, v202
	s_mov_b32 s5, 0x41a00000
	v_cmp_nlt_f32_e32 vcc, s5, v4
	s_and_saveexec_b64 s[10:11], vcc
	s_cbranch_execz .LBB0_314
	v_mul_f32_e32 v5, 0x3fb8aa3b, v4
	v_rndne_f32_e32 v6, v5
	v_sub_f32_e32 v7, v5, v6
	v_fma_f32 v5, v4, s88, -v5
	v_fmac_f32_e32 v5, 0x32a5705f, v4
	v_add_f32_e32 v5, v7, v5
	v_exp_f32_e32 v5, v5
	v_cvt_i32_f32_e32 v6, v6
	v_cmp_ngt_f32_e64 s[6:7], s79, v4
	s_mov_b32 s5, 0xc1700000
	v_cmp_ngt_f32_e32 vcc, s5, v4
	v_ldexp_f32 v5, v5, v6
	v_cndmask_b32_e64 v5, 0, v5, s[6:7]
	v_cmp_nlt_f32_e64 s[6:7], s54, v4
	s_nop 1
	v_cndmask_b32_e64 v4, v210, v5, s[6:7]
	s_and_saveexec_b64 s[12:13], vcc
	s_cbranch_execz .LBB0_313
	v_add_f32_e32 v4, 1.0, v4
	v_cmp_gt_f32_e32 vcc, s57, v4
	s_mov_b32 s5, 0x3f317217
	s_nop 0
	v_cndmask_b32_e64 v5, 0, 32, vcc
	v_ldexp_f32 v4, v4, v5
	v_log_f32_e32 v4, v4
	s_nop 0
	v_mul_f32_e32 v5, 0x3f317217, v4
	v_fma_f32 v5, v4, s5, -v5
	v_fmac_f32_e32 v5, 0x3377d1cf, v4
	s_mov_b32 s5, 0x7f800000
	v_fmac_f32_e32 v5, 0x3f317217, v4
	v_cmp_lt_f32_e64 s[6:7], |v4|, s5
	s_nop 1
	v_cndmask_b32_e64 v4, v4, v5, s[6:7]
	v_cndmask_b32_e32 v5, 0, v205, vcc
	v_sub_f32_e32 v4, v4, v5

; DI void dn_prep_item(const Params& p, int l, int item, int next_item, u32x4 (&pre)[12], unsigned char* lds, int tid) {
;     ...
;         const float sp = (a > 20.f) ? a : ((a < -15.f) ? expf(a) : logf(1.f + expf(a)));
;         float x = -expf(alog) * sp;
; #pragma unroll
;         for (int o = 1; o < 64; o <<= 1) { const float v = __shfl_up(x, o); if (lane >= o) x += v; }
;         Gs[tid] = x; BETAs[tid] = 1.f / (1.f + expf(-bb)); EGs[tid] = expf(x);
.LBB0_314:
	s_or_b64 exec, exec, s[10:11]
	v_add_u32_e32 v6, -1, v206
	v_cmp_lt_i32_e32 vcc, v6, v35
	v_mul_f32_e64 v5, v4, -v200
	v_add_u32_e32 v7, -2, v206
	v_cndmask_b32_e32 v6, v6, v206, vcc
	v_lshlrev_b32_e32 v6, 2, v6
	ds_bpermute_b32 v6, v6, v5
	v_cmp_eq_u32_e32 vcc, 0, v30
	s_waitcnt lgkmcnt(0)
	v_fma_f32 v4, v4, -v200, v6
	v_cndmask_b32_e32 v4, v4, v5, vcc
	v_cmp_lt_i32_e32 vcc, v7, v35
	v_mul_f32_e32 v6, 0xbfb8aa3b, v203
	s_nop 0
	v_cndmask_b32_e32 v5, v7, v206, vcc
	v_lshlrev_b32_e32 v5, 2, v5
	ds_bpermute_b32 v5, v5, v4
	v_cmp_gt_u32_e32 vcc, 2, v30
	v_rndne_f32_e32 v7, v6
	v_sub_f32_e32 v8, v6, v7
	v_fma_f32 v6, v203, s58, -v6
	s_waitcnt lgkmcnt(0)
	v_add_f32_e32 v5, v4, v5
	v_cndmask_b32_e32 v4, v5, v4, vcc
	v_add_u32_e32 v5, -4, v206
	v_cmp_lt_i32_e32 vcc, v5, v35
	v_fmac_f32_e32 v6, 0xb2a5705f, v203
	v_add_f32_e32 v6, v8, v6
	v_cndmask_b32_e32 v5, v5, v206, vcc
	v_lshlrev_b32_e32 v5, 2, v5
	ds_bpermute_b32 v5, v5, v4
	v_cmp_gt_u32_e32 vcc, 4, v30
	v_exp_f32_e32 v6, v6
	v_cvt_i32_f32_e32 v7, v7
	v_lshlrev_b32_e32 v8, 2, v54
	s_waitcnt lgkmcnt(0)
	v_add_f32_e32 v5, v4, v5
	v_cndmask_b32_e32 v4, v5, v4, vcc
	v_add_u32_e32 v5, -8, v206
	v_cmp_lt_i32_e32 vcc, v5, v35
	v_add_u32_e32 v9, v68, v8
	s_nop 0
	v_cndmask_b32_e32 v5, v5, v206, vcc
	v_lshlrev_b32_e32 v5, 2, v5
	ds_bpermute_b32 v5, v5, v4
	v_cmp_gt_u32_e32 vcc, 8, v30
	s_waitcnt lgkmcnt(0)
	v_add_f32_e32 v5, v4, v5
	v_cndmask_b32_e32 v4, v5, v4, vcc
	v_add_u32_e32 v5, -16, v206
	v_cmp_lt_i32_e32 vcc, v5, v35
	s_nop 1
	v_cndmask_b32_e32 v5, v5, v206, vcc
	v_lshlrev_b32_e32 v5, 2, v5
	ds_bpermute_b32 v5, v5, v4
	v_cmp_gt_u32_e32 vcc, 16, v30
	s_waitcnt lgkmcnt(0)
	v_add_f32_e32 v5, v4, v5
	v_cndmask_b32_e32 v4, v5, v4, vcc
	v_subrev_u32_e32 v5, 32, v206
	v_cmp_lt_i32_e32 vcc, v5, v35
	s_nop 1
	v_cndmask_b32_e32 v5, v5, v206, vcc
	v_lshlrev_b32_e32 v5, 2, v5
	ds_bpermute_b32 v5, v5, v4
	v_cmp_gt_u32_e32 vcc, 32, v30
	s_waitcnt lgkmcnt(0)
	v_add_f32_e32 v5, v4, v5
	v_cndmask_b32_e32 v4, v5, v4, vcc
	v_ldexp_f32 v5, v6, v7
	v_cmp_nlt_f32_e32 vcc, s59, v203
	ds_write_b32 v9, v4
	s_nop 0
	v_cndmask_b32_e32 v5, 0, v5, vcc
	v_cmp_ngt_f32_e32 vcc, s55, v203
	s_nop 1
	v_cndmask_b32_e32 v5, v210, v5, vcc
	v_add_f32_e32 v5, 1.0, v5
	v_div_scale_f32 v6, s[6:7], v5, v5, 1.0
	v_rcp_f32_e32 v7, v6
	s_nop 0
	v_fma_f32 v9, -v6, v7, 1.0
	v_fmac_f32_e32 v7, v9, v7
	v_div_scale_f32 v9, vcc, 1.0, v5, 1.0
	v_mul_f32_e32 v10, v9, v7
	v_fma_f32 v11, -v6, v10, v9
	v_fmac_f32_e32 v10, v11, v7
	v_fma_f32 v6, -v6, v10, v9
	v_div_fmas_f32 v6, v6, v7, v10
	v_mul_f32_e32 v7, 0x3fb8aa3b, v4
	v_fma_f32 v9, v4, s88, -v7
	v_rndne_f32_e32 v10, v7
	v_fmac_f32_e32 v9, 0x32a5705f, v4
	v_sub_f32_e32 v7, v7, v10
	v_add_f32_e32 v7, v7, v9
	v_exp_f32_e32 v7, v7
	v_cvt_i32_f32_e32 v9, v10
	v_div_fixup_f32 v5, v6, v5, 1.0
	v_add_u32_e32 v6, v69, v8
	ds_write_b32 v6, v5
	v_ldexp_f32 v5, v7, v9
	v_cmp_ngt_f32_e32 vcc, s79, v4
	s_nop 1
	v_cndmask_b32_e32 v5, 0, v5, vcc
	v_cmp_nlt_f32_e32 vcc, s54, v4
	s_nop 1
	v_cndmask_b32_e32 v4, v210, v5, vcc
	v_add_u32_e32 v5, v70, v8
	ds_write_b32 v5, v4

; DI void dn_prep_item(const Params& p, int l, int item, int next_item, u32x4 (&pre)[12], unsigned char* lds, int tid) {
;     ...
;         {
;             const int c = tid & 127, rg = tid >> 7;
;             float xt[32];
; #pragma unroll
;             for (int k = 0; k < 32; ++k) xt[k] = XS[k * 129 + c];
; #pragma unroll
;             for (int ii = 0; ii < 8; ++ii) { const int i = rg * 8 + ii; float a0 = XS[(32 + i) * 129 + c], a1 = 0.f;
; #pragma unroll
;                 for (int k = 0; k < 32; k += 2) { a0 -= Zs[i * 33 + k] * xt[k]; a1 -= Zs[i * 33 + k + 1] * xt[k + 1]; }
;                 XS[(32 + i) * 129 + c] = a0 + a1; }
.LBB0_503:
	s_or_b64 exec, exec, s[8:9]
	v_ashrrev_i32_e32 v35, 4, v54
	v_and_b32_e32 v2, 0x7f, v54
	v_and_b32_e32 v38, -8, v35
	s_movk_i32 s12, 0x204
	v_lshl_add_u32 v36, v2, 2, v50
	v_mul_lo_u32 v40, v38, s12
	s_movk_i32 s5, 0x84
	v_add_u32_e32 v41, v36, v40
	v_mad_u64_u32 v[38:39], s[6:7], v38, s5, v[52:53]
	s_waitcnt lgkmcnt(0)
	s_barrier
	v_lshrrev_b32_e32 v38, 7, v54
	v_mul_u32_u24_e32 v38, 0x480, v38
	v_add_u32_e32 v38, v38, v52
	ds_read2_b32 v[32:33], v36 offset1:129
	v_add_u32_e32 v39, 0x400, v36
	ds_read2_b32 v[30:31], v39 offset0:2 offset1:131
	v_add_u32_e32 v39, 0x800, v36
	ds_read2_b32 v[28:29], v39 offset0:4 offset1:133
	v_add_u32_e32 v39, 0xc00, v36
	ds_read2_b32 v[26:27], v39 offset0:6 offset1:135
	v_add_u32_e32 v39, 0x1000, v36
	ds_read2_b32 v[24:25], v39 offset0:8 offset1:137
	v_add_u32_e32 v39, 0x1400, v36
	ds_read2_b32 v[22:23], v39 offset0:10 offset1:139
	v_add_u32_e32 v39, 0x1800, v36
	ds_read2_b32 v[20:21], v39 offset0:12 offset1:141
	v_add_u32_e32 v39, 0x1c00, v36
	ds_read2_b32 v[18:19], v39 offset0:14 offset1:143
	v_add_u32_e32 v39, 0x2000, v36
	ds_read2_b32 v[16:17], v39 offset0:16 offset1:145
	v_add_u32_e32 v39, 0x2400, v36
	ds_read2_b32 v[14:15], v39 offset0:18 offset1:147
	v_add_u32_e32 v39, 0x2800, v36
	ds_read2_b32 v[12:13], v39 offset0:20 offset1:149
	v_add_u32_e32 v39, 0x2c00, v36
	ds_read2_b32 v[10:11], v39 offset0:22 offset1:151
	v_add_u32_e32 v39, 0x3000, v36
	ds_read2_b32 v[8:9], v39 offset0:24 offset1:153
	v_add_u32_e32 v39, 0x3400, v36
	ds_read2_b32 v[6:7], v39 offset0:26 offset1:155
	v_add_u32_e32 v39, 0x3800, v36
	ds_read2_b32 v[4:5], v39 offset0:28 offset1:157
	v_add_u32_e32 v39, 0x3c00, v36
	ds_read2_b32 v[2:3], v39 offset0:30 offset1:159
	ds_read_b32 v244, v41 offset:16512
	ds_read_b32 v245, v41 offset:17028
	ds_read_b32 v246, v41 offset:17544
	ds_read_b32 v247, v41 offset:18060
	ds_read_b32 v248, v41 offset:18576
	ds_read_b32 v249, v41 offset:19092
	ds_read_b32 v250, v41 offset:19608
	ds_read_b32 v251, v41 offset:20124
	ds_read_b128 v[212:215], v38 offset:0
	ds_read_b128 v[216:219], v38 offset:16
	ds_read_b128 v[220:223], v38 offset:32
	ds_read_b128 v[224:227], v38 offset:48
	ds_read_b128 v[228:231], v38 offset:64
	ds_read_b128 v[232:235], v38 offset:80
	ds_read_b128 v[236:239], v38 offset:96
	ds_read_b128 v[240:243], v38 offset:112
	ds_read_b128 v[126:129], v38 offset:144
	ds_read_b128 v[130:133], v38 offset:160
	ds_read_b128 v[134:137], v38 offset:176
	ds_read_b128 v[138:141], v38 offset:192
	ds_read_b128 v[154:157], v38 offset:208
	ds_read_b128 v[188:191], v38 offset:224
	ds_read_b128 v[192:195], v38 offset:240
	ds_read_b128 v[196:199], v38 offset:256
	s_waitcnt lgkmcnt(8)
	v_fma_f32 v244, -v32, v212, v244
	v_fma_f32 v252, -v33, v213, 0
	v_fma_f32 v244, -v30, v214, v244
	v_fma_f32 v252, -v31, v215, v252
	v_fma_f32 v244, -v28, v216, v244
	v_fma_f32 v252, -v29, v217, v252
	v_fma_f32 v244, -v26, v218, v244
	v_fma_f32 v252, -v27, v219, v252
	v_fma_f32 v244, -v24, v220, v244
	v_fma_f32 v252, -v25, v221, v252
	v_fma_f32 v244, -v22, v222, v244
	v_fma_f32 v252, -v23, v223, v252
	v_fma_f32 v244, -v20, v224, v244
	v_fma_f32 v252, -v21, v225, v252
	v_fma_f32 v244, -v18, v226, v244
	v_fma_f32 v252, -v19, v227, v252
	v_fma_f32 v244, -v16, v228, v244
	v_fma_f32 v252, -v17, v229, v252
	v_fma_f32 v244, -v14, v230, v244
	v_fma_f32 v252, -v15, v231, v252
	v_fma_f32 v244, -v12, v232, v244
	v_fma_f32 v252, -v13, v233, v252
	v_fma_f32 v244, -v10, v234, v244
	v_fma_f32 v252, -v11, v235, v252
	v_fma_f32 v244, -v8, v236, v244
	v_fma_f32 v252, -v9, v237, v252
	v_fma_f32 v244, -v6, v238, v244
	v_fma_f32 v252, -v7, v239, v252
	v_fma_f32 v244, -v4, v240, v244
	v_fma_f32 v252, -v5, v241, v252
	v_fma_f32 v244, -v2, v242, v244
	v_fma_f32 v252, -v3, v243, v252
	v_add_f32_e32 v244, v244, v252
	ds_write_b32 v41, v244 offset:16512
	ds_read_b128 v[212:215], v38 offset:288
	ds_read_b128 v[216:219], v38 offset:304
	ds_read_b128 v[220:223], v38 offset:320
	ds_read_b128 v[224:227], v38 offset:336
	ds_read_b128 v[228:231], v38 offset:352
	ds_read_b128 v[232:235], v38 offset:368
	ds_read_b128 v[236:239], v38 offset:384
	ds_read_b128 v[240:243], v38 offset:400
	s_waitcnt lgkmcnt(9)
	v_fma_f32 v245, -v32, v126, v245
	v_fma_f32 v253, -v33, v127, 0
	v_fma_f32 v245, -v30, v128, v245
	v_fma_f32 v253, -v31, v129, v253
	v_fma_f32 v245, -v28, v130, v245
	v_fma_f32 v253, -v29, v131, v253
	v_fma_f32 v245, -v26, v132, v245
	v_fma_f32 v253, -v27, v133, v253
	v_fma_f32 v245, -v24, v134, v245
	v_fma_f32 v253, -v25, v135, v253
	v_fma_f32 v245, -v22, v136, v245
	v_fma_f32 v253, -v23, v137, v253
	v_fma_f32 v245, -v20, v138, v245
	v_fma_f32 v253, -v21, v139, v253
	v_fma_f32 v245, -v18, v140, v245
	v_fma_f32 v253, -v19, v141, v253
	v_fma_f32 v245, -v16, v154, v245
	v_fma_f32 v253, -v17, v155, v253
	v_fma_f32 v245, -v14, v156, v245
	v_fma_f32 v253, -v15, v157, v253
	v_fma_f32 v245, -v12, v188, v245
	v_fma_f32 v253, -v13, v189, v253
	v_fma_f32 v245, -v10, v190, v245
	v_fma_f32 v253, -v11, v191, v253
	v_fma_f32 v245, -v8, v192, v245
	v_fma_f32 v253, -v9, v193, v253
	v_fma_f32 v245, -v6, v194, v245
	v_fma_f32 v253, -v7, v195, v253
	v_fma_f32 v245, -v4, v196, v245
	v_fma_f32 v253, -v5, v197, v253
	v_fma_f32 v245, -v2, v198, v245
	v_fma_f32 v253, -v3, v199, v253
	v_add_f32_e32 v245, v245, v253
	ds_write_b32 v41, v245 offset:17028
	ds_read_b128 v[126:129], v38 offset:432
	ds_read_b128 v[130:133], v38 offset:448
	ds_read_b128 v[134:137], v38 offset:464
	ds_read_b128 v[138:141], v38 offset:480
	ds_read_b128 v[154:157], v38 offset:496
	ds_read_b128 v[188:191], v38 offset:512
	ds_read_b128 v[192:195], v38 offset:528
	ds_read_b128 v[196:199], v38 offset:544
	s_waitcnt lgkmcnt(9)
; DI void dn_prep_item(const Params& p, int l, int item, int next_item, u32x4 (&pre)[12], unsigned char* lds, int tid) {
;     ...
;             for (int ii = 0; ii < 8; ++ii) { const int i = rg * 8 + ii; float a0 = XS[(32 + i) * 129 + c], a1 = 0.f;
; #pragma unroll
;                 for (int k = 0; k < 32; k += 2) { a0 -= Zs[i * 33 + k] * xt[k]; a1 -= Zs[i * 33 + k + 1] * xt[k + 1]; }
;                 XS[(32 + i) * 129 + c] = a0 + a1; }
	v_fma_f32 v246, -v32, v212, v246
	v_fma_f32 v252, -v33, v213, 0
	v_fma_f32 v246, -v30, v214, v246
	v_fma_f32 v252, -v31, v215, v252
	v_fma_f32 v246, -v28, v216, v246
	v_fma_f32 v252, -v29, v217, v252
	v_fma_f32 v246, -v26, v218, v246
	v_fma_f32 v252, -v27, v219, v252
	v_fma_f32 v246, -v24, v220, v246
	v_fma_f32 v252, -v25, v221, v252
	v_fma_f32 v246, -v22, v222, v246
	v_fma_f32 v252, -v23, v223, v252
	v_fma_f32 v246, -v20, v224, v246
	v_fma_f32 v252, -v21, v225, v252
	v_fma_f32 v246, -v18, v226, v246
	v_fma_f32 v252, -v19, v227, v252
	v_fma_f32 v246, -v16, v228, v246
	v_fma_f32 v252, -v17, v229, v252
	v_fma_f32 v246, -v14, v230, v246
	v_fma_f32 v252, -v15, v231, v252
	v_fma_f32 v246, -v12, v232, v246
	v_fma_f32 v252, -v13, v233, v252
	v_fma_f32 v246, -v10, v234, v246
	v_fma_f32 v252, -v11, v235, v252
	v_fma_f32 v246, -v8, v236, v246
	v_fma_f32 v252, -v9, v237, v252
	v_fma_f32 v246, -v6, v238, v246
	v_fma_f32 v252, -v7, v239, v252
	v_fma_f32 v246, -v4, v240, v246
	v_fma_f32 v252, -v5, v241, v252
	v_fma_f32 v246, -v2, v242, v246
	v_fma_f32 v252, -v3, v243, v252
	v_add_f32_e32 v246, v246, v252
	ds_write_b32 v41, v246 offset:17544
	ds_read_b128 v[212:215], v38 offset:576
	ds_read_b128 v[216:219], v38 offset:592
	ds_read_b128 v[220:223], v38 offset:608
	ds_read_b128 v[224:227], v38 offset:624
	ds_read_b128 v[228:231], v38 offset:640
	ds_read_b128 v[232:235], v38 offset:656
	ds_read_b128 v[236:239], v38 offset:672
	ds_read_b128 v[240:243], v38 offset:688
	s_waitcnt lgkmcnt(9)
	v_fma_f32 v247, -v32, v126, v247
	v_fma_f32 v253, -v33, v127, 0
	v_fma_f32 v247, -v30, v128, v247
	v_fma_f32 v253, -v31, v129, v253
	v_fma_f32 v247, -v28, v130, v247
	v_fma_f32 v253, -v29, v131, v253
	v_fma_f32 v247, -v26, v132, v247
	v_fma_f32 v253, -v27, v133, v253
	v_fma_f32 v247, -v24, v134, v247
	v_fma_f32 v253, -v25, v135, v253
	v_fma_f32 v247, -v22, v136, v247
	v_fma_f32 v253, -v23, v137, v253
	v_fma_f32 v247, -v20, v138, v247
	v_fma_f32 v253, -v21, v139, v253
	v_fma_f32 v247, -v18, v140, v247
	v_fma_f32 v253, -v19, v141, v253
	v_fma_f32 v247, -v16, v154, v247
	v_fma_f32 v253, -v17, v155, v253
	v_fma_f32 v247, -v14, v156, v247
	v_fma_f32 v253, -v15, v157, v253
	v_fma_f32 v247, -v12, v188, v247
	v_fma_f32 v253, -v13, v189, v253
	v_fma_f32 v247, -v10, v190, v247
	v_fma_f32 v253, -v11, v191, v253
	v_fma_f32 v247, -v8, v192, v247
	v_fma_f32 v253, -v9, v193, v253
	v_fma_f32 v247, -v6, v194, v247
	v_fma_f32 v253, -v7, v195, v253
	v_fma_f32 v247, -v4, v196, v247
	v_fma_f32 v253, -v5, v197, v253
	v_fma_f32 v247, -v2, v198, v247
	v_fma_f32 v253, -v3, v199, v253
	v_add_f32_e32 v247, v247, v253
	ds_write_b32 v41, v247 offset:18060
	ds_read_b128 v[126:129], v38 offset:720
	ds_read_b128 v[130:133], v38 offset:736
	ds_read_b128 v[134:137], v38 offset:752
	ds_read_b128 v[138:141], v38 offset:768
	ds_read_b128 v[154:157], v38 offset:784
	ds_read_b128 v[188:191], v38 offset:800
	ds_read_b128 v[192:195], v38 offset:816
	ds_read_b128 v[196:199], v38 offset:832
	s_waitcnt lgkmcnt(9)
	v_fma_f32 v248, -v32, v212, v248
	v_fma_f32 v252, -v33, v213, 0
	v_fma_f32 v248, -v30, v214, v248
	v_fma_f32 v252, -v31, v215, v252
	v_fma_f32 v248, -v28, v216, v248
	v_fma_f32 v252, -v29, v217, v252
	v_fma_f32 v248, -v26, v218, v248
	v_fma_f32 v252, -v27, v219, v252
	v_fma_f32 v248, -v24, v220, v248
	v_fma_f32 v252, -v25, v221, v252
	v_fma_f32 v248, -v22, v222, v248
	v_fma_f32 v252, -v23, v223, v252
	v_fma_f32 v248, -v20, v224, v248
	v_fma_f32 v252, -v21, v225, v252
	v_fma_f32 v248, -v18, v226, v248
	v_fma_f32 v252, -v19, v227, v252
	v_fma_f32 v248, -v16, v228, v248
	v_fma_f32 v252, -v17, v229, v252
	v_fma_f32 v248, -v14, v230, v248
	v_fma_f32 v252, -v15, v231, v252
	v_fma_f32 v248, -v12, v232, v248
	v_fma_f32 v252, -v13, v233, v252
	v_fma_f32 v248, -v10, v234, v248
	v_fma_f32 v252, -v11, v235, v252
	v_fma_f32 v248, -v8, v236, v248
	v_fma_f32 v252, -v9, v237, v252
	v_fma_f32 v248, -v6, v238, v248
	v_fma_f32 v252, -v7, v239, v252
	v_fma_f32 v248, -v4, v240, v248
	v_fma_f32 v252, -v5, v241, v252
	v_fma_f32 v248, -v2, v242, v248
	v_fma_f32 v252, -v3, v243, v252
	v_add_f32_e32 v248, v248, v252
	ds_write_b32 v41, v248 offset:18576
	ds_read_b128 v[212:215], v38 offset:864
	ds_read_b128 v[216:219], v38 offset:880
	ds_read_b128 v[220:223], v38 offset:896
	ds_read_b128 v[224:227], v38 offset:912
	ds_read_b128 v[228:231], v38 offset:928
	ds_read_b128 v[232:235], v38 offset:944
	ds_read_b128 v[236:239], v38 offset:960
	ds_read_b128 v[240:243], v38 offset:976
	s_waitcnt lgkmcnt(9)
	v_fma_f32 v249, -v32, v126, v249
	v_fma_f32 v253, -v33, v127, 0
	v_fma_f32 v249, -v30, v128, v249
	v_fma_f32 v253, -v31, v129, v253
	v_fma_f32 v249, -v28, v130, v249
	v_fma_f32 v253, -v29, v131, v253
	v_fma_f32 v249, -v26, v132, v249
	v_fma_f32 v253, -v27, v133, v253
	v_fma_f32 v249, -v24, v134, v249
	v_fma_f32 v253, -v25, v135, v253
	v_fma_f32 v249, -v22, v136, v249
	v_fma_f32 v253, -v23, v137, v253
	v_fma_f32 v249, -v20, v138, v249
	v_fma_f32 v253, -v21, v139, v253
	v_fma_f32 v249, -v18, v140, v249
	v_fma_f32 v253, -v19, v141, v253
	v_fma_f32 v249, -v16, v154, v249
	v_fma_f32 v253, -v17, v155, v253
	v_fma_f32 v249, -v14, v156, v249
	v_fma_f32 v253, -v15, v157, v253
	v_fma_f32 v249, -v12, v188, v249
	v_fma_f32 v253, -v13, v189, v253
	v_fma_f32 v249, -v10, v190, v249
	v_fma_f32 v253, -v11, v191, v253
	v_fma_f32 v249, -v8, v192, v249
	v_fma_f32 v253, -v9, v193, v253
	v_fma_f32 v249, -v6, v194, v249
	v_fma_f32 v253, -v7, v195, v253
	v_fma_f32 v249, -v4, v196, v249
	v_fma_f32 v253, -v5, v197, v253
	v_fma_f32 v249, -v2, v198, v249
	v_fma_f32 v253, -v3, v199, v253
	v_add_f32_e32 v249, v249, v253
	ds_write_b32 v41, v249 offset:19092
	ds_read_b128 v[126:129], v38 offset:1008
	ds_read_b128 v[130:133], v38 offset:1024
	ds_read_b128 v[134:137], v38 offset:1040
	ds_read_b128 v[138:141], v38 offset:1056
	ds_read_b128 v[154:157], v38 offset:1072
	ds_read_b128 v[188:191], v38 offset:1088
	ds_read_b128 v[192:195], v38 offset:1104
	ds_read_b128 v[196:199], v38 offset:1120
	s_waitcnt lgkmcnt(9)
; DI unsigned pk2(float lo, float hi) { f32x2_t v = {lo, hi}; bf16x2_t b = __builtin_convertvector(v, bf16x2_t); return __builtin_bit_cast(unsigned, b); }
; DI void dn_prep_fetch(const Params& p, int item, int tid, u32x4 (&pre)[12]) {
;     const int h = item & 7, n = (item >> 3) & 31, b = item >> 8, i = tid >> 3, d0 = (tid & 7) * 8;
;     const bf16_t* DQKV = (const bf16_t*)(p.ws + OFF_DQKV);
; #pragma unroll
;     for (int mat = 0; mat < 3; ++mat)
; #pragma unroll
;         for (int j = 0; j < 4; ++j) { int t = n * 64 + i - 3 + j; t = t < 0 ? 0 : t; pre[mat * 4 + j] = *(const u32x4*)(DQKV + (size_t)(b * SEQL + t) * 1536 + mat * 512 + h * 64 + d0); }
; DI void dn_prep_item(const Params& p, int l, int item, int next_item, u32x4 (&pre)[12], unsigned char* lds, int tid) {
;     ...
;             for (int ii = 0; ii < 8; ++ii) { const int i = rg * 8 + ii; float a0 = XS[(32 + i) * 129 + c], a1 = 0.f;
; #pragma unroll
;                 for (int k = 0; k < 32; k += 2) { a0 -= Zs[i * 33 + k] * xt[k]; a1 -= Zs[i * 33 + k + 1] * xt[k + 1]; }
;                 XS[(32 + i) * 129 + c] = a0 + a1; }
;         }
;     }
;     __syncthreads();
;     dn_prep_fetch(p, next_item < 2048 ? next_item : item, tid, pre);
;     {
;         const int chunk = (b * 8 + h) * 32 + n; unsigned char* base = p.ws + OFF_U + (size_t)chunk * PREP_CHUNK_BYTES;
;         const int f = tid >> 6, m = f >> 1, s = f & 1, r = lane & 15, g = lane >> 4, row = 16 * m + r, c0 = 32 * s + 4 * g, c1 = c0 + 16;
;         u32x4 w;
;         { const float* a = XS + row * 129 + 64; w.x = pk2(a[c0], a[c0 + 1]); w.y = pk2(a[c0 + 2], a[c0 + 3]); w.z = pk2(a[c1], a[c1 + 1]); w.w = pk2(a[c1 + 2], a[c1 + 3]); *(u32x4*)(base + (size_t)tid * 16) = w; }
; #pragma unroll
;         for (int q = 0; q < 2; ++q) { const int idx = tid * 2 + q, wm = idx >> 6, ln = idx & 63, vv = 16 * (wm >> 2) + (ln & 15), r0 = 16 * (wm & 3) + 4 * (ln >> 4);
;             u32x2 o; o.x = pk2(XS[r0 * 129 + vv], XS[(r0 + 1) * 129 + vv]); o.y = pk2(XS[(r0 + 2) * 129 + vv], XS[(r0 + 3) * 129 + vv]); *(u32x2*)(base + 32768 + (size_t)idx * 8) = o; }
;         if (tid == 0) ((float*)(p.ws + OFF_CD))[chunk] = EGs[63];
	v_fma_f32 v250, -v32, v212, v250
	v_fma_f32 v252, -v33, v213, 0
	v_fma_f32 v250, -v30, v214, v250
	v_fma_f32 v252, -v31, v215, v252
	v_fma_f32 v250, -v28, v216, v250
	v_fma_f32 v252, -v29, v217, v252
	v_fma_f32 v250, -v26, v218, v250
	v_fma_f32 v252, -v27, v219, v252
	v_fma_f32 v250, -v24, v220, v250
	v_fma_f32 v252, -v25, v221, v252
	v_fma_f32 v250, -v22, v222, v250
	v_fma_f32 v252, -v23, v223, v252
	v_fma_f32 v250, -v20, v224, v250
	v_fma_f32 v252, -v21, v225, v252
	v_fma_f32 v250, -v18, v226, v250
	v_fma_f32 v252, -v19, v227, v252
	v_fma_f32 v250, -v16, v228, v250
	v_fma_f32 v252, -v17, v229, v252
	v_fma_f32 v250, -v14, v230, v250
	v_fma_f32 v252, -v15, v231, v252
	v_fma_f32 v250, -v12, v232, v250
	v_fma_f32 v252, -v13, v233, v252
	v_fma_f32 v250, -v10, v234, v250
	v_fma_f32 v252, -v11, v235, v252
	v_fma_f32 v250, -v8, v236, v250
	v_fma_f32 v252, -v9, v237, v252
	v_fma_f32 v250, -v6, v238, v250
	v_fma_f32 v252, -v7, v239, v252
	v_fma_f32 v250, -v4, v240, v250
	v_fma_f32 v252, -v5, v241, v252
	v_fma_f32 v250, -v2, v242, v250
	v_fma_f32 v252, -v3, v243, v252
	v_add_f32_e32 v250, v250, v252
	ds_write_b32 v41, v250 offset:19608
	s_waitcnt lgkmcnt(1)
	v_fma_f32 v251, -v32, v126, v251
	v_fma_f32 v253, -v33, v127, 0
	v_fma_f32 v251, -v30, v128, v251
	v_fma_f32 v253, -v31, v129, v253
	v_fma_f32 v251, -v28, v130, v251
	v_fma_f32 v253, -v29, v131, v253
	v_fma_f32 v251, -v26, v132, v251
	v_fma_f32 v253, -v27, v133, v253
	v_fma_f32 v251, -v24, v134, v251
	v_fma_f32 v253, -v25, v135, v253
	v_fma_f32 v251, -v22, v136, v251
	v_fma_f32 v253, -v23, v137, v253
	v_fma_f32 v251, -v20, v138, v251
	v_fma_f32 v253, -v21, v139, v253
	v_fma_f32 v251, -v18, v140, v251
	v_fma_f32 v253, -v19, v141, v253
	v_fma_f32 v251, -v16, v154, v251
	v_fma_f32 v253, -v17, v155, v253
	v_fma_f32 v251, -v14, v156, v251
	v_fma_f32 v253, -v15, v157, v253
	v_fma_f32 v251, -v12, v188, v251
	v_fma_f32 v253, -v13, v189, v253
	v_fma_f32 v251, -v10, v190, v251
	v_fma_f32 v253, -v11, v191, v253
	v_fma_f32 v251, -v8, v192, v251
	v_fma_f32 v253, -v9, v193, v253
	v_fma_f32 v251, -v6, v194, v251
	v_fma_f32 v253, -v7, v195, v253
	v_fma_f32 v251, -v4, v196, v251
	v_fma_f32 v253, -v5, v197, v253
	v_fma_f32 v251, -v2, v198, v251
	v_fma_f32 v253, -v3, v199, v253
	v_add_f32_e32 v251, v251, v253
	ds_write_b32 v41, v251 offset:20124
	s_add_i32 s4, s42, s33
	s_cmpk_gt_i32 s4, 0x7ff
	v_and_b32_e32 v66, -16, v77
	v_lshl_add_u64 v[62:63], s[26:27], 0, v[58:59]
	v_or_b32_e32 v58, v66, v61
	v_ashrrev_i32_e32 v57, 31, v56
	s_cselect_b64 s[6:7], -1, 0
	s_cmpk_lt_i32 s4, 0x800
	s_cselect_b32 s5, s4, s42
	s_lshl_b32 s8, s5, 3
	s_lshl_b32 s5, s5, 7
	s_and_b32 s10, s8, 0x7c0
	s_and_b32 s11, s8, 0xfffff800
	s_and_b32 s5, s5, 0x380
	s_add_u32 s8, s29, s5
	s_addc_u32 s9, s40, 0
	v_mov_b32_e32 v35, v165
	s_movk_i32 s5, 0xc00
	v_add_u32_e32 v10, s10, v77
	v_max_i32_e32 v10, 0, v10
	v_add_u32_e32 v10, s11, v10
	v_add3_u32 v8, s10, -3, v77
	v_max_i32_e32 v4, 0, v8
	v_max_i32_e32 v6, -1, v8
	v_max_i32_e32 v8, -2, v8
	v_lshl_add_u64 v[2:3], s[8:9], 0, v[34:35]
	v_add_u32_e32 v4, s11, v4
	v_add3_u32 v6, v6, s11, 1
	v_add3_u32 v8, v8, s11, 2
	v_mad_i64_i32 v[4:5], s[8:9], v4, s5, v[2:3]
	v_mad_i64_i32 v[6:7], s[8:9], v6, s5, v[2:3]
	v_mad_i64_i32 v[8:9], s[8:9], v8, s5, v[2:3]
	v_mad_i64_i32 v[2:3], s[8:9], v10, s5, v[2:3]
	s_waitcnt lgkmcnt(0)
	s_barrier
	global_load_dwordx4 v[46:49], v[4:5], off
	global_load_dwordx4 v[42:45], v[6:7], off
	global_load_dwordx4 v[38:41], v[8:9], off
	global_load_dwordx4 v[34:37], v[2:3], off
	global_load_dwordx4 v[30:33], v[4:5], off offset:1024
	global_load_dwordx4 v[26:29], v[6:7], off offset:1024
	global_load_dwordx4 v[22:25], v[8:9], off offset:1024
	global_load_dwordx4 v[18:21], v[2:3], off offset:1024
	global_load_dwordx4 v[14:17], v[4:5], off offset:2048
	global_load_dwordx4 v[10:13], v[6:7], off offset:2048
	s_nop 0
	global_load_dwordx4 v[6:9], v[8:9], off offset:2048
	s_nop 0
	global_load_dwordx4 v[2:5], v[2:3], off offset:2048
	s_cmpk_lt_i32 s4, 0x800
	s_cselect_b32 s5, s4, s42
	s_ashr_i32 s8, s5, 8
	s_lshl_b32 s8, s8, 11
	s_bfe_u32 s9, s5, 0x50003
	s_lshl_b32 s9, s9, 6
	s_or_b32 s8, s8, s9
	s_and_b32 s9, s5, 7
	s_lshl_b32 s9, s9, 2
	v_and_b32_e32 v142, 63, v166
	v_add_u32_e32 v142, s8, v142
	v_lshlrev_b32_e32 v142, 6, v142
	v_add_u32_e32 v142, s9, v142
	global_load_dword v202, v142, s[16:17]
	global_load_dword v203, v142, s[16:17] offset:32
	v_mad_u64_u32 v[58:59], s[8:9], v58, s12, v[50:51]
	v_lshlrev_b32_e32 v59, 7, v60
	v_and_b32_e32 v59, 0x80, v59
	v_and_b32_e32 v60, 48, v54
	v_add3_u32 v64, v58, v59, v60
	ds_read2_b32 v[58:59], v64 offset0:64 offset1:65
	ds_read2_b32 v[60:61], v64 offset0:66 offset1:67
	s_waitcnt lgkmcnt(1)
	v_cvt_pk_bf16_f32 v58, v58, v59
	s_waitcnt lgkmcnt(0)
	v_cvt_pk_bf16_f32 v59, v60, v61
	ds_read2_b32 v[60:61], v64 offset0:80 offset1:81
	ds_read2_b32 v[64:65], v64 offset0:82 offset1:83
	s_waitcnt lgkmcnt(1)
	v_cvt_pk_bf16_f32 v60, v60, v61
	s_waitcnt lgkmcnt(0)
	v_cvt_pk_bf16_f32 v61, v64, v65
	v_lshl_add_u64 v[64:65], v[54:55], 4, v[62:63]
	v_lshrrev_b32_e32 v55, 1, v54
	global_store_dwordx4 v[64:65], v[58:61], off
	v_and_b32_e32 v55, 48, v55
	s_nop 0
	v_lshrrev_b32_e32 v58, 2, v56
	v_and_or_b32 v55, v58, 12, v55
	v_mul_u32_u24_e32 v55, 0x81, v55
	v_and_b32_e32 v58, 14, v56
	v_lshl_add_u32 v58, v58, 2, v50
	v_lshlrev_b32_e32 v59, 2, v66
	v_lshlrev_b32_e32 v55, 2, v55
	v_add3_u32 v55, v58, v59, v55
	ds_read2_b32 v[60:61], v55 offset1:1
	ds_read2_b32 v[64:65], v55 offset0:129 offset1:130
	v_add_u32_e32 v59, 0x408, v55
	v_add_u32_e32 v55, 0x60c, v55
	ds_read2_b32 v[66:67], v59 offset1:1
	ds_read2_b32 v[78:79], v55 offset1:1
	v_lshl_add_u64 v[56:57], v[56:57], 3, v[62:63]
	v_add_co_u32_e32 v56, vcc, 0x8000, v56
	s_waitcnt lgkmcnt(2)
	v_cvt_pk_bf16_f32 v58, v60, v64
	v_addc_co_u32_e32 v57, vcc, 0, v57, vcc
	s_waitcnt lgkmcnt(0)
	v_cvt_pk_bf16_f32 v59, v66, v78
	v_cvt_pk_bf16_f32 v60, v61, v65
	v_cvt_pk_bf16_f32 v61, v67, v79
	v_cmp_eq_u32_e32 vcc, 0, v54
	global_store_dwordx4 v[56:57], v[58:61], off
	s_and_saveexec_b64 s[8:9], vcc
	s_cbranch_execz .LBB0_280
	ds_read_b32 v54, v76
	v_lshl_add_u64 v[0:1], v[0:1], 2, s[38:39]
	s_waitcnt lgkmcnt(0)
	global_store_dword v[0:1], v54, off
	s_branch .LBB0_280
